# barrier edits + P2 plain stores + P4 last-unit write-through xg2 stores
# baseline (speedup 1.0000x reference)
; __device__ __forceinline__ unsigned cvt_pk(float lo, float hi) { f32x2_t v = {lo, hi}; bf16x2_t b = __builtin_convertvector(v, bf16x2_t); return __builtin_bit_cast(unsigned, b); }
;     __device__ __forceinline__ void operator()(AccRef acc, const pg8::Unit& u, int wr, int wc, int fr, int fq) const {
;         const int row0 = u.pm * 256 + wr * 64 + fr, col0 = u.pn * 256 + wc * 32 + 8 * fq;
; #pragma unroll
;         for (int ai = 0; ai < 2; ++ai)
; #pragma unroll
;             for (int m = 0; m < 4; ++m) { bf16* rowp = O + (size_t)(row0 + ai * 128 + m * 16) * INW + col0;
; #pragma unroll
;                 for (int bj = 0; bj < 2; ++bj) { const f32x4 v0 = acc[ai][bj][m][0], v1 = acc[ai][bj][m][1];
;                     v4u w; w.x = cvt_pk(v0[0], v0[1]); w.y = cvt_pk(v0[2], v0[3]); w.z = cvt_pk(v1[0], v1[1]); w.w = cvt_pk(v1[2], v1[3]);
;                     { v4u* pp_ = (v4u*)(rowp + bj * 128); asm volatile("global_store_dwordx4 %0, %1, off sc1\n\ts_nop 2" :: "v"(pp_), "v"(w) : "memory"); } } }
.LBB0_165:
	v_lshl_add_u32 v142, s46, 8, v1
	v_lshl_or_b32 v150, s2, 8, v145
	v_ashrrev_i32_e32 v143, 31, v142
	v_ashrrev_i32_e32 v151, 31, v150
	v_lshlrev_b64 v[152:153], 12, v[142:143]
	v_lshl_add_u64 v[152:153], s[24:25], 0, v[152:153]
	v_lshlrev_b64 v[154:155], 1, v[150:151]
	v_cvt_pk_bf16_f32 v150, v126, v127
	v_lshl_add_u64 v[156:157], v[152:153], 0, v[154:155]
	v_cvt_pk_bf16_f32 v151, v128, v129
	v_cvt_pk_bf16_f32 v152, v122, v123
	v_cvt_pk_bf16_f32 v153, v124, v125
	global_store_dwordx4 v[156:157], v[150:153], off
	s_nop 2
	v_cvt_pk_bf16_f32 v150, v114, v115
	v_cvt_pk_bf16_f32 v151, v116, v117
	v_cvt_pk_bf16_f32 v152, v106, v107
	v_cvt_pk_bf16_f32 v153, v108, v109
	v_lshl_add_u64 v[158:159], v[156:157], 0, s[8:9]
	global_store_dwordx4 v[158:159], v[150:153], off
	s_nop 2
	v_or_b32_e32 v150, 16, v142
	v_ashrrev_i32_e32 v151, 31, v150
	v_lshlrev_b64 v[150:151], 12, v[150:151]
	v_lshl_add_u64 v[150:151], s[24:25], 0, v[150:151]
	v_lshl_add_u64 v[158:159], v[150:151], 0, v[154:155]
	v_cvt_pk_bf16_f32 v150, v118, v119
	v_cvt_pk_bf16_f32 v151, v120, v121
	v_cvt_pk_bf16_f32 v152, v110, v111
	v_cvt_pk_bf16_f32 v153, v112, v113
	global_store_dwordx4 v[158:159], v[150:153], off
	s_nop 2
	v_cvt_pk_bf16_f32 v150, v98, v99
	v_cvt_pk_bf16_f32 v151, v100, v101
	v_cvt_pk_bf16_f32 v152, v90, v91
	v_cvt_pk_bf16_f32 v153, v92, v93
	v_lshl_add_u64 v[158:159], v[158:159], 0, s[8:9]
	global_store_dwordx4 v[158:159], v[150:153], off
	s_nop 2
	v_or_b32_e32 v150, 32, v142
	v_ashrrev_i32_e32 v151, 31, v150
	v_lshlrev_b64 v[150:151], 12, v[150:151]
	v_lshl_add_u64 v[150:151], s[24:25], 0, v[150:151]
	v_lshl_add_u64 v[158:159], v[150:151], 0, v[154:155]
	v_cvt_pk_bf16_f32 v150, v102, v103
	v_cvt_pk_bf16_f32 v151, v104, v105
	v_cvt_pk_bf16_f32 v152, v94, v95
	v_cvt_pk_bf16_f32 v153, v96, v97
	global_store_dwordx4 v[158:159], v[150:153], off
	s_nop 2
	v_cvt_pk_bf16_f32 v150, v82, v83
	v_cvt_pk_bf16_f32 v151, v84, v85
	v_cvt_pk_bf16_f32 v152, v74, v75
	v_cvt_pk_bf16_f32 v153, v76, v77
	v_lshl_add_u64 v[158:159], v[158:159], 0, s[8:9]
	global_store_dwordx4 v[158:159], v[150:153], off
	s_nop 2
	v_or_b32_e32 v150, 48, v142
	v_ashrrev_i32_e32 v151, 31, v150
	v_lshlrev_b64 v[150:151], 12, v[150:151]
	v_lshl_add_u64 v[150:151], s[24:25], 0, v[150:151]
	v_lshl_add_u64 v[154:155], v[150:151], 0, v[154:155]
	v_cvt_pk_bf16_f32 v150, v86, v87
	v_cvt_pk_bf16_f32 v151, v88, v89
	v_cvt_pk_bf16_f32 v152, v78, v79
	v_cvt_pk_bf16_f32 v153, v80, v81
	global_store_dwordx4 v[154:155], v[150:153], off
	s_nop 2
	v_cvt_pk_bf16_f32 v150, v70, v71
	v_cvt_pk_bf16_f32 v151, v72, v73
	v_cvt_pk_bf16_f32 v152, v66, v67
	v_cvt_pk_bf16_f32 v153, v68, v69
	v_lshl_add_u64 v[154:155], v[154:155], 0, s[8:9]
	global_store_dwordx4 v[154:155], v[150:153], off
	s_nop 2
	s_mov_b64 s[46:47], 0x80000
	v_lshl_add_u64 v[154:155], v[156:157], 0, s[46:47]
	v_cvt_pk_bf16_f32 v150, v62, v63
	v_cvt_pk_bf16_f32 v151, v64, v65
	v_cvt_pk_bf16_f32 v152, v58, v59
	v_cvt_pk_bf16_f32 v153, v60, v61
	global_store_dwordx4 v[154:155], v[150:153], off
	s_nop 2
	s_mov_b64 s[46:47], 0x80100
	v_cvt_pk_bf16_f32 v150, v50, v51
	v_cvt_pk_bf16_f32 v151, v52, v53
	v_cvt_pk_bf16_f32 v152, v42, v43
	v_cvt_pk_bf16_f32 v153, v44, v45
	v_lshl_add_u64 v[154:155], v[156:157], 0, s[46:47]
	global_store_dwordx4 v[154:155], v[150:153], off
	s_nop 2
	s_mov_b64 s[46:47], 0x90000
	v_lshl_add_u64 v[154:155], v[156:157], 0, s[46:47]
	v_cvt_pk_bf16_f32 v150, v54, v55
	v_cvt_pk_bf16_f32 v151, v56, v57
	v_cvt_pk_bf16_f32 v152, v46, v47
	v_cvt_pk_bf16_f32 v153, v48, v49
	global_store_dwordx4 v[154:155], v[150:153], off
	s_nop 2
	s_mov_b64 s[46:47], 0x90100
	v_cvt_pk_bf16_f32 v150, v34, v35
	v_cvt_pk_bf16_f32 v151, v36, v37
	v_cvt_pk_bf16_f32 v152, v26, v27
	v_cvt_pk_bf16_f32 v153, v28, v29
	v_lshl_add_u64 v[154:155], v[156:157], 0, s[46:47]
	global_store_dwordx4 v[154:155], v[150:153], off
	s_nop 2
	s_mov_b64 s[46:47], 0xa0000
	v_lshl_add_u64 v[154:155], v[156:157], 0, s[46:47]
	v_cvt_pk_bf16_f32 v150, v38, v39
	v_cvt_pk_bf16_f32 v151, v40, v41
	v_cvt_pk_bf16_f32 v152, v30, v31
	v_cvt_pk_bf16_f32 v153, v32, v33
	global_store_dwordx4 v[154:155], v[150:153], off
	s_nop 2
	s_mov_b64 s[46:47], 0xa0100
	v_cvt_pk_bf16_f32 v150, v18, v19
	v_cvt_pk_bf16_f32 v151, v20, v21
	v_cvt_pk_bf16_f32 v152, v10, v11
	v_cvt_pk_bf16_f32 v153, v12, v13
	v_lshl_add_u64 v[154:155], v[156:157], 0, s[46:47]
	global_store_dwordx4 v[154:155], v[150:153], off
	s_nop 2
	s_mov_b64 s[46:47], 0xb0000
	v_lshl_add_u64 v[154:155], v[156:157], 0, s[46:47]
	v_cvt_pk_bf16_f32 v150, v22, v23
	v_cvt_pk_bf16_f32 v151, v24, v25
	v_cvt_pk_bf16_f32 v152, v14, v15
	v_cvt_pk_bf16_f32 v153, v16, v17
	global_store_dwordx4 v[154:155], v[150:153], off
	s_nop 2
	s_mov_b64 s[46:47], 0xb0100
	v_cvt_pk_bf16_f32 v150, v6, v7
	v_cvt_pk_bf16_f32 v151, v8, v9
	v_cvt_pk_bf16_f32 v152, v2, v3
	v_cvt_pk_bf16_f32 v153, v4, v5
	v_lshl_add_u64 v[154:155], v[156:157], 0, s[46:47]
	global_store_dwordx4 v[154:155], v[150:153], off
	s_nop 2
	s_cmp_gt_i32 s2, 3
	s_cbranch_scc1 .LBB0_169
;     __device__ __forceinline__ void operator()(AccRef acc, const pg8::Unit& u, int wr, int wc, int fr, int fq) const {
;     ...
;                     for (int bj = 0; bj < 2; ++bj) { const f32x4 v0 = acc[ai][bj][m][0], v1 = acc[ai][bj][m][1];
;                         sr[ai][m][bj] = red_sum_16_32(((v0[0] * v0[0] + v0[1] * v0[1]) + (v0[2] * v0[2] + v0[3] * v0[3])) + ((v1[0] * v1[0] + v1[1] * v1[1]) + (v1[2] * v1[2] + v1[3] * v1[3]))); }
	v_mul_f32_e32 v127, v127, v127
	v_mul_f32_e32 v123, v123, v123
	v_fmac_f32_e32 v127, v126, v126
	v_mul_f32_e32 v126, v129, v129
	v_fmac_f32_e32 v123, v122, v122
	v_mul_f32_e32 v122, v125, v125
	v_fmac_f32_e32 v126, v128, v128
	v_fmac_f32_e32 v122, v124, v124
	v_mul_f32_e32 v107, v107, v107
	v_add_f32_e32 v126, v127, v126
	v_add_f32_e32 v122, v123, v122
	v_mul_f32_e32 v115, v115, v115
	v_fmac_f32_e32 v107, v106, v106
	v_mul_f32_e32 v106, v109, v109
	v_add_f32_e32 v122, v126, v122
	v_fmac_f32_e32 v115, v114, v114
	v_mul_f32_e32 v114, v117, v117
	v_fmac_f32_e32 v106, v108, v108
	v_mul_f32_e32 v108, v119, v119
	v_mul_f32_e32 v109, v121, v121
	v_mov_b32_e32 v123, v122
	v_fmac_f32_e32 v114, v116, v116
	v_fmac_f32_e32 v108, v118, v118
	v_fmac_f32_e32 v109, v120, v120
	s_nop 1
	v_permlane16_swap_b32 v123, v122
	v_add_f32_e32 v114, v115, v114
	v_add_f32_e32 v106, v107, v106
	v_add_f32_e32 v108, v108, v109
	v_mul_f32_e32 v109, v111, v111
	v_add_f32_e32 v122, v123, v122
	v_add_f32_e32 v106, v114, v106
	v_fmac_f32_e32 v109, v110, v110
	v_mul_f32_e32 v110, v113, v113
	v_mov_b32_e32 v123, v122
	v_mov_b32_e32 v107, v106
	v_fmac_f32_e32 v110, v112, v112
	v_mul_f32_e32 v91, v91, v91
	s_nop 1
	v_permlane32_swap_b32 v123, v122
	s_nop 1
	v_permlane16_swap_b32 v107, v106
	v_add_f32_e32 v109, v109, v110
	v_mul_f32_e32 v99, v99, v99
	v_fmac_f32_e32 v91, v90, v90
	v_mul_f32_e32 v90, v93, v93
	v_add_f32_e32 v106, v107, v106
	v_add_f32_e32 v108, v108, v109
	v_fmac_f32_e32 v99, v98, v98
	v_mul_f32_e32 v98, v101, v101
	v_fmac_f32_e32 v90, v92, v92
	v_mul_f32_e32 v92, v103, v103
	v_mul_f32_e32 v93, v105, v105
	v_mov_b32_e32 v107, v106
	v_mov_b32_e32 v109, v108
	v_fmac_f32_e32 v98, v100, v100
	v_fmac_f32_e32 v92, v102, v102
	v_fmac_f32_e32 v93, v104, v104
	s_nop 1
	v_permlane32_swap_b32 v107, v106
	s_nop 1
	v_permlane16_swap_b32 v109, v108
	v_add_f32_e32 v98, v99, v98
	v_add_f32_e32 v90, v91, v90
	v_add_f32_e32 v92, v92, v93
	v_mul_f32_e32 v93, v95, v95
	v_add_f32_e32 v108, v109, v108
	v_add_f32_e32 v90, v98, v90
	v_fmac_f32_e32 v93, v94, v94
	v_mul_f32_e32 v94, v97, v97
	v_mov_b32_e32 v109, v108
	v_mov_b32_e32 v91, v90
	v_fmac_f32_e32 v94, v96, v96
	v_mul_f32_e32 v75, v75, v75
	s_nop 1
	v_permlane32_swap_b32 v109, v108
	s_nop 1
	v_permlane16_swap_b32 v91, v90
	v_add_f32_e32 v93, v93, v94
	v_mul_f32_e32 v83, v83, v83
	v_fmac_f32_e32 v75, v74, v74
	v_mul_f32_e32 v74, v77, v77
	v_add_f32_e32 v90, v91, v90
	v_add_f32_e32 v92, v92, v93
	v_fmac_f32_e32 v83, v82, v82
	v_mul_f32_e32 v82, v85, v85
	v_fmac_f32_e32 v74, v76, v76
	v_mul_f32_e32 v76, v87, v87
	v_mul_f32_e32 v77, v89, v89
	v_mov_b32_e32 v91, v90
	v_mov_b32_e32 v93, v92
	v_fmac_f32_e32 v82, v84, v84
	v_fmac_f32_e32 v76, v86, v86
	v_fmac_f32_e32 v77, v88, v88
	s_nop 1
	v_permlane32_swap_b32 v91, v90
	s_nop 1
	v_permlane16_swap_b32 v93, v92
	v_add_f32_e32 v82, v83, v82
	v_add_f32_e32 v74, v75, v74
	v_add_f32_e32 v76, v76, v77
	v_mul_f32_e32 v77, v79, v79
	v_add_f32_e32 v92, v93, v92
	v_add_f32_e32 v74, v82, v74
	v_fmac_f32_e32 v77, v78, v78
	v_mul_f32_e32 v78, v81, v81
	v_mov_b32_e32 v93, v92
	v_mov_b32_e32 v75, v74
	v_fmac_f32_e32 v78, v80, v80
	s_nop 1
	v_permlane32_swap_b32 v93, v92
	s_nop 1
	v_permlane16_swap_b32 v75, v74
	v_add_f32_e32 v77, v77, v78
	v_mul_f32_e32 v71, v71, v71
	v_mul_f32_e32 v67, v67, v67
	v_add_f32_e32 v74, v75, v74
	v_add_f32_e32 v76, v76, v77
	v_fmac_f32_e32 v71, v70, v70
	v_mul_f32_e32 v70, v73, v73
	v_fmac_f32_e32 v67, v66, v66
	v_mul_f32_e32 v66, v69, v69
	v_mov_b32_e32 v75, v74
	v_mov_b32_e32 v77, v76
	v_fmac_f32_e32 v70, v72, v72
	v_fmac_f32_e32 v66, v68, v68
	s_nop 1
	v_permlane32_swap_b32 v75, v74
	s_nop 1
	v_permlane16_swap_b32 v77, v76
	v_add_f32_e32 v70, v71, v70
	v_add_f32_e32 v66, v67, v66
	v_mul_f32_e32 v63, v63, v63
	v_mul_f32_e32 v59, v59, v59
	v_add_f32_e32 v76, v77, v76
	v_add_f32_e32 v66, v70, v66
	v_fmac_f32_e32 v63, v62, v62
	v_mul_f32_e32 v62, v65, v65
	v_fmac_f32_e32 v59, v58, v58
	v_mul_f32_e32 v58, v61, v61
	v_mov_b32_e32 v77, v76
	v_mov_b32_e32 v67, v66
	v_fmac_f32_e32 v62, v64, v64
	v_fmac_f32_e32 v58, v60, v60
	v_mul_f32_e32 v43, v43, v43
	s_nop 1
	v_permlane32_swap_b32 v77, v76
	s_nop 1
	v_permlane16_swap_b32 v67, v66
	v_add_f32_e32 v62, v63, v62
	v_add_f32_e32 v58, v59, v58
	v_mul_f32_e32 v51, v51, v51
	v_fmac_f32_e32 v43, v42, v42
	v_mul_f32_e32 v42, v45, v45
	v_add_f32_e32 v66, v67, v66
	v_add_f32_e32 v58, v62, v58
	v_fmac_f32_e32 v51, v50, v50
	v_mul_f32_e32 v50, v53, v53
	v_fmac_f32_e32 v42, v44, v44
	v_mul_f32_e32 v44, v55, v55
	v_mul_f32_e32 v45, v57, v57
	v_mov_b32_e32 v67, v66
	v_mov_b32_e32 v59, v58
	v_fmac_f32_e32 v50, v52, v52
	v_fmac_f32_e32 v44, v54, v54
	v_fmac_f32_e32 v45, v56, v56
	s_nop 1
	v_permlane32_swap_b32 v67, v66
	s_nop 1
	v_permlane16_swap_b32 v59, v58
	v_add_f32_e32 v50, v51, v50
;     __device__ __forceinline__ void operator()(AccRef acc, const pg8::Unit& u, int wr, int wc, int fr, int fq) const {
;     ...
;                         sr[ai][m][bj] = red_sum_16_32(((v0[0] * v0[0] + v0[1] * v0[1]) + (v0[2] * v0[2] + v0[3] * v0[3])) + ((v1[0] * v1[0] + v1[1] * v1[1]) + (v1[2] * v1[2] + v1[3] * v1[3]))); }
;             if (fq == 0) {
; #pragma unroll
;                 for (int ai = 0; ai < 2; ++ai)
; #pragma unroll
;                     for (int m = 0; m < 4; ++m)
; #pragma unroll
;                         for (int bj = 0; bj < 2; ++bj) atomicAdd(hss + (size_t)(4 * u.pn + 2 * bj + (wc >> 1)) * MT + pm0 * 256 + row0 + ai * 128 + m * 16, sr[ai][m][bj] * asc);
	v_add_f32_e32 v42, v43, v42
	v_add_f32_e32 v44, v44, v45
	v_mul_f32_e32 v45, v47, v47
	v_add_f32_e32 v58, v59, v58
	v_add_f32_e32 v42, v50, v42
	v_fmac_f32_e32 v45, v46, v46
	v_mul_f32_e32 v46, v49, v49
	v_mov_b32_e32 v59, v58
	v_mov_b32_e32 v43, v42
	v_fmac_f32_e32 v46, v48, v48
	v_mul_f32_e32 v27, v27, v27
	s_nop 1
	v_permlane32_swap_b32 v59, v58
	s_nop 1
	v_permlane16_swap_b32 v43, v42
	v_add_f32_e32 v45, v45, v46
	v_mul_f32_e32 v35, v35, v35
	v_fmac_f32_e32 v27, v26, v26
	v_mul_f32_e32 v26, v29, v29
	v_add_f32_e32 v42, v43, v42
	v_add_f32_e32 v44, v44, v45
	v_fmac_f32_e32 v35, v34, v34
	v_mul_f32_e32 v34, v37, v37
	v_fmac_f32_e32 v26, v28, v28
	v_mul_f32_e32 v28, v39, v39
	v_mul_f32_e32 v29, v41, v41
	v_mov_b32_e32 v43, v42
	v_mov_b32_e32 v45, v44
	v_fmac_f32_e32 v34, v36, v36
	v_fmac_f32_e32 v28, v38, v38
	v_fmac_f32_e32 v29, v40, v40
	s_nop 1
	v_permlane32_swap_b32 v43, v42
	s_nop 1
	v_permlane16_swap_b32 v45, v44
	v_add_f32_e32 v34, v35, v34
	v_add_f32_e32 v26, v27, v26
	v_add_f32_e32 v28, v28, v29
	v_mul_f32_e32 v29, v31, v31
	v_add_f32_e32 v44, v45, v44
	v_add_f32_e32 v26, v34, v26
	v_fmac_f32_e32 v29, v30, v30
	v_mul_f32_e32 v30, v33, v33
	v_mov_b32_e32 v45, v44
	v_mov_b32_e32 v27, v26
	v_fmac_f32_e32 v30, v32, v32
	v_mul_f32_e32 v11, v11, v11
	s_nop 1
	v_permlane32_swap_b32 v45, v44
	s_nop 1
	v_permlane16_swap_b32 v27, v26
	v_add_f32_e32 v29, v29, v30
	v_mul_f32_e32 v19, v19, v19
	v_fmac_f32_e32 v11, v10, v10
	v_mul_f32_e32 v10, v13, v13
	v_add_f32_e32 v26, v27, v26
	v_add_f32_e32 v28, v28, v29
	v_fmac_f32_e32 v19, v18, v18
	v_mul_f32_e32 v18, v21, v21
	v_fmac_f32_e32 v10, v12, v12
	v_mul_f32_e32 v12, v23, v23
	v_mul_f32_e32 v13, v25, v25
	v_mov_b32_e32 v27, v26
	v_mov_b32_e32 v29, v28
	v_fmac_f32_e32 v18, v20, v20
	v_fmac_f32_e32 v12, v22, v22
	v_fmac_f32_e32 v13, v24, v24
	s_nop 1
	v_permlane32_swap_b32 v27, v26
	s_nop 1
	v_permlane16_swap_b32 v29, v28
	v_add_f32_e32 v18, v19, v18
	v_add_f32_e32 v10, v11, v10
	v_add_f32_e32 v12, v12, v13
	v_mul_f32_e32 v13, v15, v15
	v_add_f32_e32 v28, v29, v28
	v_add_f32_e32 v10, v18, v10
	v_fmac_f32_e32 v13, v14, v14
	v_mul_f32_e32 v14, v17, v17
	v_mov_b32_e32 v29, v28
	v_mov_b32_e32 v11, v10
	v_fmac_f32_e32 v14, v16, v16
	s_nop 1
	v_permlane32_swap_b32 v29, v28
	s_nop 1
	v_permlane16_swap_b32 v11, v10
	v_add_f32_e32 v13, v13, v14
	v_mul_f32_e32 v7, v7, v7
	v_mul_f32_e32 v3, v3, v3
	v_add_f32_e32 v10, v11, v10
	v_add_f32_e32 v12, v12, v13
	v_fmac_f32_e32 v7, v6, v6
	v_mul_f32_e32 v6, v9, v9
	v_fmac_f32_e32 v3, v2, v2
	v_mul_f32_e32 v2, v5, v5
	v_mov_b32_e32 v11, v10
	v_mov_b32_e32 v13, v12
	v_fmac_f32_e32 v6, v8, v8
	v_fmac_f32_e32 v2, v4, v4
	s_nop 1
	v_permlane32_swap_b32 v11, v10
	s_nop 1
	v_permlane16_swap_b32 v13, v12
	v_add_f32_e32 v6, v7, v6
	v_add_f32_e32 v2, v3, v2
	v_add_f32_e32 v12, v13, v12
	v_add_f32_e32 v2, v6, v2
	v_mov_b32_e32 v13, v12
	v_mov_b32_e32 v3, v2
	s_nop 1
	v_permlane32_swap_b32 v13, v12
	s_nop 1
	v_permlane16_swap_b32 v3, v2
	s_nop 0
	v_add_f32_e32 v2, v3, v2
	v_mov_b32_e32 v3, v2
	s_nop 1
	v_permlane32_swap_b32 v3, v2
	s_and_saveexec_b64 s[46:47], s[0:1]
	s_cbranch_execz .LBB0_168
	s_lshl_b32 s2, s2, 2
	s_or_b32 s2, s2, s56
	s_ashr_i32 s3, s2, 31
	s_lshl_b64 s[48:49], s[2:3], 17
	s_add_u32 s48, s33, s48
	s_addc_u32 s49, s40, s49
	s_or_b32 s2, s2, 2
	s_ashr_i32 s3, s2, 31
	s_lshl_b64 s[2:3], s[2:3], 17
	v_add_f32_e32 v6, v3, v2
	v_lshlrev_b64 v[2:3], 2, v[142:143]
	s_add_u32 s2, s33, s2
	v_add_f32_e32 v21, v123, v122
	v_lshl_add_u64 v[4:5], s[48:49], 0, v[2:3]
	s_addc_u32 s3, s40, s3
	v_add_f32_e32 v20, v107, v106
	global_atomic_add_f32 v[4:5], v21, off
	v_lshl_add_u64 v[2:3], s[2:3], 0, v[2:3]
	v_add_f32_e32 v7, v13, v12
	v_add_f32_e32 v8, v11, v10
	v_add_f32_e32 v9, v29, v28
	v_add_f32_e32 v10, v27, v26
	v_add_f32_e32 v11, v45, v44
	v_add_f32_e32 v12, v43, v42
	v_add_f32_e32 v13, v59, v58
	v_add_f32_e32 v14, v67, v66
	v_add_f32_e32 v15, v77, v76
	v_add_f32_e32 v16, v75, v74
	v_add_f32_e32 v17, v93, v92
	v_add_f32_e32 v18, v91, v90
	v_add_f32_e32 v19, v109, v108
	global_atomic_add_f32 v[2:3], v20, off
	global_atomic_add_f32 v[4:5], v19, off offset:64
	global_atomic_add_f32 v[2:3], v18, off offset:64
	global_atomic_add_f32 v[4:5], v17, off offset:128
	global_atomic_add_f32 v[2:3], v16, off offset:128
	global_atomic_add_f32 v[4:5], v15, off offset:192
	global_atomic_add_f32 v[2:3], v14, off offset:192
	global_atomic_add_f32 v[4:5], v13, off offset:512
	global_atomic_add_f32 v[2:3], v12, off offset:512
	global_atomic_add_f32 v[4:5], v11, off offset:576
	global_atomic_add_f32 v[2:3], v10, off offset:576
	global_atomic_add_f32 v[4:5], v9, off offset:640
	global_atomic_add_f32 v[2:3], v8, off offset:640
	global_atomic_add_f32 v[4:5], v7, off offset:704
	global_atomic_add_f32 v[2:3], v6, off offset:704

;     __device__ bool next(int i, pg8::Unit& u) const { const int L = i * cph + k; if (L >= nunits) return false; const int nig = 8 * nN, gid = L / nig, w = L % nig; u.pm = 16 * xh + 8 * gid + (w & 7); u.pn = w >> 3; return true; }
; template <class Epi, class Sched, bool ALIGN_EPI = false, bool SP2 = false>
; __device__ __forceinline__ void gemm_phase(PG8_LAS unsigned char* lds, const Gemm g, const Sched& S, const Epi& E, volatile PG8_LAS unsigned* sw = nullptr) {
;     ...
;         const bool has_next = S.next(ui + 1, nxt);
.LBB0_441:
	s_add_i32 s64, s64, 1
	s_mul_i32 s9, s64, s76
	s_add_i32 s9, s9, s97
	s_cmp_lt_i32 s9, 64
	s_cselect_b64 s[26:27], -1, 0
	s_cselect_b32 s98, 0, 1
	s_cmp_gt_i32 s9, 63
	s_cbranch_scc1 .LBB0_443
	s_ashr_i32 s8, s9, 31
	s_lshr_b32 s8, s8, 27
	s_add_i32 s8, s9, s8
	s_ashr_i32 s22, s8, 5
	s_andn2_b32 s8, s8, 31
	s_sub_i32 s9, s9, s8
	s_lshl_b32 s8, s22, 3
	s_add_i32 s8, s8, s77
	s_and_b32 s22, s9, 7
	s_or_b32 s8, s8, s22
	s_ashr_i32 s22, s9, 3

; __device__ __forceinline__ unsigned cvt_pk(float lo, float hi) { f32x2_t v = {lo, hi}; bf16x2_t b = __builtin_convertvector(v, bf16x2_t); return __builtin_bit_cast(unsigned, b); }
; #define EO_LOADG(bj) do { _Pragma("unroll") for (int n = 0; n < 2; ++n) { const int c_ = u.pn * 256 + (bj) * 128 + cl + 4 * n; g1a[bj][n] = *(const f32x4*)(g1t + b * D + c_); G2a[bj][n] = *(const f32x4*)(G2t + b * D + c_); } } while (0)
; #define EO_LOADB(k) do { _Pragma("unroll") for (int mm = 0; mm < 2; ++mm) { const char* xr = xb + (size_t)(((((k) >> 1) & 1) * 128 + (2 * ((k) & 1) + mm) * 16) * D + ((k) >> 2) * 128) * 4; \
;             xv[(k) & 1][mm][0] = *(const f32x4*)(xr + loff); xv[(k) & 1][mm][1] = *(const f32x4*)(xr + 16 + loff); } } while (0)
;     __device__ __forceinline__ void operator()(AccRef acc, const pg8::Unit& u, int wr, int wc, int fr_, int fq_) const {
;     ...
;         f32x4 xv[2][2][2], g1a[2][2], G2a[2][2];
;     ...
;         EO_LOADG(0); EO_LOADB(0);
; #pragma unroll
;         for (int k = 0; k < 8; ++k) {
;             const int bj = k >> 2, ai = (k >> 1) & 1;
;             if (k + 1 < 8) EO_LOADB(k + 1);
;             if (k == 3) EO_LOADG(1);
;             asm volatile("" ::: "memory");
; #pragma unroll
;             for (int mm = 0; mm < 2; ++mm) { const int m = 2 * (k & 1) + mm;
;                 const f32x4 v0 = xv[k & 1][mm][0] + g1a[bj][0] * acc[ai][bj][m][0], v1 = xv[k & 1][mm][1] + g1a[bj][1] * acc[ai][bj][m][1];
;                 ss[ai][m] += ((v0[0] * v0[0] + v0[1] * v0[1]) + (v0[2] * v0[2] + v0[3] * v0[3])) + ((v1[0] * v1[0] + v1[1] * v1[1]) + (v1[2] * v1[2] + v1[3] * v1[3]));
;                 const f32x4 h0 = v0 * G2a[bj][0], h1 = v1 * G2a[bj][1]; v4u w; w.x = cvt_pk(h0[0], h0[1]); w.y = cvt_pk(h0[2], h0[3]); w.z = cvt_pk(h1[0], h1[1]); w.w = cvt_pk(h1[2], h1[3]);
;                 *(v4u*)(xgb + (size_t)((2 * bj) << 15) + (size_t)((ai * 128 + m * 16) * 128) + xgl) = w;
;             }
.LBB0_451:
	s_sub_i32 s23, s46, 64
	s_lshr_b32 s23, s23, 5
	s_lshr_b32 s9, s46, 3
	s_add_i32 s23, s23, 8
	s_and_b64 s[50:51], s[50:51], exec
	s_cselect_b32 s9, s9, s23
	s_ashr_i32 s31, s30, 31
	s_lshl_b64 s[50:51], s[30:31], 10
	s_lshl_b32 s23, s65, 4
	s_lshl_b32 s31, s30, 2
	s_add_i32 s23, s23, s31
	s_or_b32 s52, s23, s55
	s_ashr_i32 s53, s52, 31
	v_lshlrev_b32_e32 v164, 3, v177
	s_lshl_b64 s[52:53], s[52:53], 15
	v_add_u32_e32 v140, s54, v164
	s_add_u32 s48, s48, s50
	s_addc_u32 s49, s49, s51
	v_lshl_add_u32 v162, s30, 8, v140
	s_lshl_b32 s30, s9, 10
	s_ashr_i32 s31, s30, 31
	v_add_u32_e32 v178, s43, v130
	s_lshl_b64 s[50:51], s[30:31], 2
	v_lshlrev_b32_e32 v141, 12, v178
	s_add_u32 s30, s66, s50
	s_addc_u32 s31, s67, s51
	v_ashrrev_i32_e32 v163, 31, v162
	v_lshl_add_u32 v154, v140, 2, v141
	v_readlane_b32 s68, v250, 36
	v_lshlrev_b64 v[138:139], 2, v[162:163]
	v_lshl_add_u64 v[160:161], s[48:49], 0, v[154:155]
	v_readlane_b32 s69, v250, 37
	s_add_u32 s50, s68, s50
	v_lshl_add_u64 v[134:135], s[30:31], 0, v[138:139]
	v_add_co_u32_e32 v168, vcc, s40, v160
	s_mov_b64 s[74:75], 0x10000
	s_addc_u32 s51, s69, s51
	global_load_dwordx4 v[130:133], v[134:135], off offset:16
	s_nop 0
	global_load_dwordx4 v[134:137], v[134:135], off
	s_nop 0
	global_load_dwordx4 v[180:183], v154, s[48:49] offset:16
	global_load_dwordx4 v[184:187], v154, s[48:49]
	v_addc_co_u32_e32 v169, vcc, 0, v161, vcc
	v_lshl_add_u64 v[140:141], v[160:161], 0, s[74:75]
	v_lshl_add_u64 v[138:139], s[50:51], 0, v[138:139]
	global_load_dwordx4 v[188:191], v[168:169], off
	global_load_dwordx4 v[192:195], v[140:141], off offset:16
	global_load_dwordx4 v[142:145], v[138:139], off
	s_nop 0
	global_load_dwordx4 v[138:141], v[138:139], off offset:16
	s_mov_b32 s9, 0x20000
	v_add_u32_e32 v163, s56, v164
	v_add_co_u32_e32 v164, vcc, s9, v160
	s_mov_b64 s[74:75], 0x20000
	s_nop 0
	v_addc_co_u32_e32 v165, vcc, 0, v161, vcc
	global_load_dwordx4 v[196:199], v[164:165], off
	v_lshl_add_u64 v[166:167], v[160:161], 0, s[74:75]
	global_load_dwordx4 v[200:203], v[166:167], off offset:16
	s_mov_b32 s9, 0x30000
	v_add_co_u32_e32 v166, vcc, s9, v160
	v_lshlrev_b32_e32 v170, 7, v178
	s_mov_b64 s[74:75], 0x30000
	v_addc_co_u32_e32 v167, vcc, 0, v161, vcc
	v_lshl_add_u32 v212, v163, 1, v170
	v_add_u32_e32 v170, 0x80, v162
	v_lshl_add_u64 v[162:163], v[160:161], 0, s[74:75]
	global_load_dwordx4 v[204:207], v[166:167], off
	global_load_dwordx4 v[208:211], v[162:163], off offset:16
	s_add_u32 s52, s71, s52
	s_addc_u32 s53, s72, s53
	s_mov_b32 s9, 0x80000
	v_mov_b32_e32 v213, v155
	v_lshl_add_u64 v[162:163], s[52:53], 0, v[212:213]
	s_waitcnt vmcnt(0)
	v_pk_fma_f32 v[124:125], v[124:125], v[132:133], v[182:183]
	v_pk_fma_f32 v[122:123], v[122:123], v[130:131], v[180:181]
	v_pk_fma_f32 v[128:129], v[128:129], v[136:137], v[186:187]
	v_pk_fma_f32 v[126:127], v[126:127], v[134:135], v[184:185]
	v_mul_f32_e32 v184, v123, v123
	v_mul_f32_e32 v185, v125, v125
	v_fmac_f32_e32 v184, v122, v122
	v_pk_fma_f32 v[180:181], v[116:117], v[132:133], v[194:195]
	v_pk_fma_f32 v[182:183], v[114:115], v[130:131], v[192:193]
	v_fmac_f32_e32 v185, v124, v124
	v_pk_mul_f32 v[116:117], v[144:145], v[128:129]
	v_pk_mul_f32 v[114:115], v[142:143], v[126:127]
	v_pk_mul_f32 v[124:125], v[140:141], v[124:125]
	v_pk_mul_f32 v[122:123], v[138:139], v[122:123]
	v_mul_f32_e32 v171, v127, v127
	v_mul_f32_e32 v179, v129, v129
	v_cvt_pk_bf16_f32 v114, v114, v115
	v_cvt_pk_bf16_f32 v115, v116, v117
	v_cvt_pk_bf16_f32 v116, v122, v123
	v_cvt_pk_bf16_f32 v117, v124, v125
	v_pk_fma_f32 v[120:121], v[120:121], v[136:137], v[190:191]
	v_pk_fma_f32 v[118:119], v[118:119], v[134:135], v[188:189]
	v_fmac_f32_e32 v171, v126, v126
	v_fmac_f32_e32 v179, v128, v128
	s_cselect_b32 s100, 1, 0
	s_cmp_lg_u32 s98, 0
	s_cbranch_scc1 .Lwt_p4_0_a
	global_store_dwordx4 v212, v[114:117], s[52:53]
	s_branch .Lwt_p4_0_b
.Lwt_p4_0_a:
	global_store_dwordx4 v212, v[114:117], s[52:53] sc1
.Lwt_p4_0_b:
	s_cmp_lg_u32 s100, 0
	v_mul_f32_e32 v186, v119, v119
	v_mul_f32_e32 v187, v121, v121
	v_mul_f32_e32 v114, v183, v183
	v_mul_f32_e32 v115, v181, v181
	v_add_f32_e32 v126, v171, v179
	v_add_f32_e32 v127, v184, v185
	v_fmac_f32_e32 v114, v182, v182
	v_fmac_f32_e32 v115, v180, v180
	v_fmac_f32_e32 v186, v118, v118
	v_add_f32_e32 v179, v126, v127
	v_fmac_f32_e32 v187, v120, v120
	v_add_f32_e32 v127, v114, v115
	v_pk_mul_f32 v[116:117], v[144:145], v[120:121]
	v_pk_mul_f32 v[114:115], v[142:143], v[118:119]
	v_pk_mul_f32 v[118:119], v[140:141], v[180:181]
	v_pk_mul_f32 v[120:121], v[138:139], v[182:183]
	v_cvt_pk_bf16_f32 v114, v114, v115
	v_cvt_pk_bf16_f32 v115, v116, v117
	v_cvt_pk_bf16_f32 v116, v120, v121
	v_cvt_pk_bf16_f32 v117, v118, v119
	s_cselect_b32 s100, 1, 0
	s_cmp_lg_u32 s98, 0
	s_cbranch_scc1 .Lwt_p4_1_a
	global_store_dwordx4 v212, v[114:117], s[52:53] offset:2048
	s_branch .Lwt_p4_1_b
.Lwt_p4_1_a:
	global_store_dwordx4 v212, v[114:117], s[52:53] offset:2048 sc1
; __device__ __forceinline__ unsigned cvt_pk(float lo, float hi) { f32x2_t v = {lo, hi}; bf16x2_t b = __builtin_convertvector(v, bf16x2_t); return __builtin_bit_cast(unsigned, b); }
; #define EO_LOADG(bj) do { _Pragma("unroll") for (int n = 0; n < 2; ++n) { const int c_ = u.pn * 256 + (bj) * 128 + cl + 4 * n; g1a[bj][n] = *(const f32x4*)(g1t + b * D + c_); G2a[bj][n] = *(const f32x4*)(G2t + b * D + c_); } } while (0)
; #define EO_LOADB(k) do { _Pragma("unroll") for (int mm = 0; mm < 2; ++mm) { const char* xr = xb + (size_t)(((((k) >> 1) & 1) * 128 + (2 * ((k) & 1) + mm) * 16) * D + ((k) >> 2) * 128) * 4; \
;             xv[(k) & 1][mm][0] = *(const f32x4*)(xr + loff); xv[(k) & 1][mm][1] = *(const f32x4*)(xr + 16 + loff); } } while (0)
;     __device__ __forceinline__ void operator()(AccRef acc, const pg8::Unit& u, int wr, int wc, int fr_, int fq_) const {
;     ...
;         EO_LOADG(0); EO_LOADB(0);
; #pragma unroll
;         for (int k = 0; k < 8; ++k) {
;             const int bj = k >> 2, ai = (k >> 1) & 1;
;             if (k + 1 < 8) EO_LOADB(k + 1);
;             if (k == 3) EO_LOADG(1);
;             asm volatile("" ::: "memory");
; #pragma unroll
;             for (int mm = 0; mm < 2; ++mm) { const int m = 2 * (k & 1) + mm;
;                 const f32x4 v0 = xv[k & 1][mm][0] + g1a[bj][0] * acc[ai][bj][m][0], v1 = xv[k & 1][mm][1] + g1a[bj][1] * acc[ai][bj][m][1];
;                 ss[ai][m] += ((v0[0] * v0[0] + v0[1] * v0[1]) + (v0[2] * v0[2] + v0[3] * v0[3])) + ((v1[0] * v1[0] + v1[1] * v1[1]) + (v1[2] * v1[2] + v1[3] * v1[3]));
;                 const f32x4 h0 = v0 * G2a[bj][0], h1 = v1 * G2a[bj][1]; v4u w; w.x = cvt_pk(h0[0], h0[1]); w.y = cvt_pk(h0[2], h0[3]); w.z = cvt_pk(h1[0], h1[1]); w.w = cvt_pk(h1[2], h1[3]);
;                 *(v4u*)(xgb + (size_t)((2 * bj) << 15) + (size_t)((ai * 128 + m * 16) * 128) + xgl) = w;
;             }
.Lwt_p4_1_b:
	s_cmp_lg_u32 s100, 0
	s_mov_b64 s[52:53], 0x80000
	v_add_f32_e32 v126, v186, v187
	v_add_co_u32_e32 v116, vcc, s9, v160
	v_lshl_add_u64 v[114:115], v[160:161], 0, s[52:53]
	s_nop 0
	v_addc_co_u32_e32 v117, vcc, 0, v161, vcc
	global_load_dwordx4 v[118:121], v[116:117], off
	global_load_dwordx4 v[122:125], v[114:115], off offset:16
	s_mov_b32 s9, 0x90000
	s_mov_b64 s[52:53], 0x90000
	v_add_co_u32_e32 v114, vcc, s9, v160
	v_lshl_add_u64 v[180:181], v[160:161], 0, s[52:53]
	s_nop 0
	v_addc_co_u32_e32 v115, vcc, 0, v161, vcc
	v_add_f32_e32 v212, v126, v127
	global_load_dwordx4 v[126:129], v[114:115], off
	s_nop 0
	global_load_dwordx4 v[180:183], v[180:181], off offset:16
	v_pk_fma_f32 v[112:113], v[112:113], v[136:137], v[198:199]
	v_pk_fma_f32 v[110:111], v[110:111], v[134:135], v[196:197]
	v_pk_fma_f32 v[184:185], v[106:107], v[130:131], v[200:201]
	v_mul_f32_e32 v106, v111, v111
	v_mul_f32_e32 v107, v113, v113
	v_pk_fma_f32 v[108:109], v[108:109], v[132:133], v[202:203]
	v_fmac_f32_e32 v106, v110, v110
	v_fmac_f32_e32 v107, v112, v112
	v_add_f32_e32 v106, v106, v107
	v_mul_f32_e32 v107, v185, v185
	v_mul_f32_e32 v171, v109, v109
	v_pk_mul_f32 v[112:113], v[144:145], v[112:113]
	s_movk_i32 s9, 0x1000
	v_fmac_f32_e32 v107, v184, v184
	v_fmac_f32_e32 v171, v108, v108
	v_pk_mul_f32 v[110:111], v[142:143], v[110:111]
	v_pk_mul_f32 v[186:187], v[140:141], v[108:109]
	v_pk_mul_f32 v[184:185], v[138:139], v[184:185]
	v_cvt_pk_bf16_f32 v109, v112, v113
	v_add_co_u32_e32 v112, vcc, s9, v162
	v_add_f32_e32 v107, v107, v171
	v_cvt_pk_bf16_f32 v108, v110, v111
	v_cvt_pk_bf16_f32 v110, v184, v185
	v_cvt_pk_bf16_f32 v111, v186, v187
	v_addc_co_u32_e32 v113, vcc, 0, v163, vcc
	v_pk_fma_f32 v[104:105], v[104:105], v[136:137], v[206:207]
	v_pk_fma_f32 v[102:103], v[102:103], v[134:135], v[204:205]
	v_add_f32_e32 v106, v106, v107
	s_cselect_b32 s100, 1, 0
	s_cmp_lg_u32 s98, 0
	s_cbranch_scc1 .Lwt_p4_2_a
	global_store_dwordx4 v[112:113], v[108:111], off
	s_branch .Lwt_p4_2_b
.Lwt_p4_2_a:
	global_store_dwordx4 v[112:113], v[108:111], off sc1
.Lwt_p4_2_b:
	s_cmp_lg_u32 s100, 0
	v_mul_f32_e32 v107, v103, v103
	v_pk_fma_f32 v[100:101], v[100:101], v[132:133], v[210:211]
	v_mul_f32_e32 v108, v105, v105
	v_pk_fma_f32 v[98:99], v[98:99], v[130:131], v[208:209]
	v_fmac_f32_e32 v107, v102, v102
	v_fmac_f32_e32 v108, v104, v104
	v_add_f32_e32 v107, v107, v108
	v_mul_f32_e32 v108, v99, v99
	v_mul_f32_e32 v109, v101, v101
	v_fmac_f32_e32 v108, v98, v98
	v_fmac_f32_e32 v109, v100, v100
	v_add_f32_e32 v108, v108, v109
	v_add_f32_e32 v107, v107, v108
	v_pk_mul_f32 v[104:105], v[144:145], v[104:105]
	v_pk_mul_f32 v[102:103], v[142:143], v[102:103]
	v_pk_mul_f32 v[108:109], v[140:141], v[100:101]
	v_pk_mul_f32 v[100:101], v[138:139], v[98:99]
	v_cvt_pk_bf16_f32 v98, v102, v103
	v_cvt_pk_bf16_f32 v99, v104, v105
	v_cvt_pk_bf16_f32 v100, v100, v101
	v_cvt_pk_bf16_f32 v101, v108, v109
	s_mov_b32 s9, 0xa0000
	s_cselect_b32 s100, 1, 0
	s_cmp_lg_u32 s98, 0
	s_cbranch_scc1 .Lwt_p4_3_a
	global_store_dwordx4 v[112:113], v[98:101], off offset:2048
	s_branch .Lwt_p4_3_b
.Lwt_p4_3_a:
	global_store_dwordx4 v[112:113], v[98:101], off offset:2048 sc1
.Lwt_p4_3_b:
	s_cmp_lg_u32 s100, 0
	s_mov_b64 s[52:53], 0xa0000
	v_ashrrev_i32_e32 v171, 31, v170
	v_add_co_u32_e32 v100, vcc, s9, v160
	v_lshl_add_u64 v[98:99], v[160:161], 0, s[52:53]
	s_nop 0
	v_addc_co_u32_e32 v101, vcc, 0, v161, vcc
	global_load_dwordx4 v[102:105], v[100:101], off
	global_load_dwordx4 v[108:111], v[98:99], off offset:16
	s_mov_b32 s9, 0xb0000
	v_add_co_u32_e32 v98, vcc, s9, v160
	s_mov_b64 s[52:53], 0xb0000
	s_nop 0
	v_addc_co_u32_e32 v99, vcc, 0, v161, vcc
	v_lshl_add_u64 v[112:113], v[160:161], 0, s[52:53]
	global_load_dwordx4 v[184:187], v[98:99], off
	global_load_dwordx4 v[188:191], v[112:113], off offset:16
	s_waitcnt vmcnt(9)
	v_pk_fma_f32 v[96:97], v[96:97], v[136:137], v[120:121]
	v_pk_fma_f32 v[94:95], v[94:95], v[134:135], v[118:119]
	s_waitcnt vmcnt(8)
	v_pk_fma_f32 v[192:193], v[90:91], v[130:131], v[122:123]
	v_mul_f32_e32 v90, v95, v95
	v_mul_f32_e32 v91, v97, v97
	v_pk_fma_f32 v[112:113], v[92:93], v[132:133], v[124:125]
	v_fmac_f32_e32 v90, v94, v94
	v_fmac_f32_e32 v91, v96, v96
	v_add_f32_e32 v196, v90, v91
	v_pk_mul_f32 v[92:93], v[144:145], v[96:97]
	v_pk_mul_f32 v[90:91], v[142:143], v[94:95]
	v_pk_mul_f32 v[94:95], v[140:141], v[112:113]
	s_movk_i32 s9, 0x4000
	v_cvt_pk_bf16_f32 v90, v90, v91
	v_cvt_pk_bf16_f32 v91, v92, v93
	v_cvt_pk_bf16_f32 v93, v94, v95
	v_add_co_u32_e32 v94, vcc, s9, v162
	s_movk_i32 s9, 0x5000
	s_nop 0
	v_addc_co_u32_e32 v95, vcc, 0, v163, vcc
	v_pk_mul_f32 v[96:97], v[138:139], v[192:193]
	v_add_co_u32_e32 v194, vcc, s9, v162
	v_cvt_pk_bf16_f32 v92, v96, v97
	s_nop 0
	v_addc_co_u32_e32 v195, vcc, 0, v163, vcc
	s_waitcnt vmcnt(7)
	v_pk_fma_f32 v[88:89], v[88:89], v[136:137], v[128:129]
	v_pk_fma_f32 v[86:87], v[86:87], v[134:135], v[126:127]
	s_waitcnt vmcnt(6)
	v_pk_fma_f32 v[126:127], v[84:85], v[132:133], v[182:183]
	v_pk_fma_f32 v[128:129], v[82:83], v[130:131], v[180:181]
	s_cselect_b32 s100, 1, 0
	s_cmp_lg_u32 s98, 0
	s_cbranch_scc1 .Lwt_p4_4_a
	global_store_dwordx4 v[194:195], v[90:93], off offset:-4096
	s_branch .Lwt_p4_4_b
.Lwt_p4_4_a:
	global_store_dwordx4 v[194:195], v[90:93], off offset:-4096 sc1
.Lwt_p4_4_b:
	s_cmp_lg_u32 s100, 0
	v_pk_mul_f32 v[84:85], v[144:145], v[88:89]
	v_pk_mul_f32 v[82:83], v[142:143], v[86:87]
	v_pk_mul_f32 v[90:91], v[140:141], v[126:127]
	v_pk_mul_f32 v[92:93], v[138:139], v[128:129]
	v_cvt_pk_bf16_f32 v82, v82, v83
	v_cvt_pk_bf16_f32 v83, v84, v85
	v_cvt_pk_bf16_f32 v84, v92, v93
	v_cvt_pk_bf16_f32 v85, v90, v91
	s_cselect_b32 s100, 1, 0
	s_cmp_lg_u32 s98, 0
	s_cbranch_scc1 .Lwt_p4_5_a
	global_store_dwordx4 v[94:95], v[82:85], off offset:2048
	s_branch .Lwt_p4_5_b
; __device__ __forceinline__ unsigned cvt_pk(float lo, float hi) { f32x2_t v = {lo, hi}; bf16x2_t b = __builtin_convertvector(v, bf16x2_t); return __builtin_bit_cast(unsigned, b); }
; #define EO_LOADG(bj) do { _Pragma("unroll") for (int n = 0; n < 2; ++n) { const int c_ = u.pn * 256 + (bj) * 128 + cl + 4 * n; g1a[bj][n] = *(const f32x4*)(g1t + b * D + c_); G2a[bj][n] = *(const f32x4*)(G2t + b * D + c_); } } while (0)
; #define EO_LOADB(k) do { _Pragma("unroll") for (int mm = 0; mm < 2; ++mm) { const char* xr = xb + (size_t)(((((k) >> 1) & 1) * 128 + (2 * ((k) & 1) + mm) * 16) * D + ((k) >> 2) * 128) * 4; \
;             xv[(k) & 1][mm][0] = *(const f32x4*)(xr + loff); xv[(k) & 1][mm][1] = *(const f32x4*)(xr + 16 + loff); } } while (0)
;     __device__ __forceinline__ void operator()(AccRef acc, const pg8::Unit& u, int wr, int wc, int fr_, int fq_) const {
;     ...
;         EO_LOADG(0); EO_LOADB(0);
; #pragma unroll
;         for (int k = 0; k < 8; ++k) {
;             const int bj = k >> 2, ai = (k >> 1) & 1;
;             if (k + 1 < 8) EO_LOADB(k + 1);
;             if (k == 3) EO_LOADG(1);
;             asm volatile("" ::: "memory");
; #pragma unroll
;             for (int mm = 0; mm < 2; ++mm) { const int m = 2 * (k & 1) + mm;
;                 const f32x4 v0 = xv[k & 1][mm][0] + g1a[bj][0] * acc[ai][bj][m][0], v1 = xv[k & 1][mm][1] + g1a[bj][1] * acc[ai][bj][m][1];
;                 ss[ai][m] += ((v0[0] * v0[0] + v0[1] * v0[1]) + (v0[2] * v0[2] + v0[3] * v0[3])) + ((v1[0] * v1[0] + v1[1] * v1[1]) + (v1[2] * v1[2] + v1[3] * v1[3]));
;                 const f32x4 h0 = v0 * G2a[bj][0], h1 = v1 * G2a[bj][1]; v4u w; w.x = cvt_pk(h0[0], h0[1]); w.y = cvt_pk(h0[2], h0[3]); w.z = cvt_pk(h1[0], h1[1]); w.w = cvt_pk(h1[2], h1[3]);
;                 *(v4u*)(xgb + (size_t)((2 * bj) << 15) + (size_t)((ai * 128 + m * 16) * 128) + xgl) = w;
;             }
.Lwt_p4_5_a:
	global_store_dwordx4 v[94:95], v[82:85], off offset:2048 sc1
.Lwt_p4_5_b:
	s_cmp_lg_u32 s100, 0
	v_mul_f32_e32 v197, v193, v193
	global_load_dwordx4 v[118:121], v154, s[48:49] offset:528
	global_load_dwordx4 v[122:125], v154, s[48:49] offset:512
	v_lshlrev_b64 v[82:83], 2, v[170:171]
	v_lshl_add_u64 v[84:85], s[30:31], 0, v[82:83]
	global_load_dwordx4 v[90:93], v[84:85], off offset:16
	global_load_dwordx4 v[94:97], v[84:85], off
	v_mul_f32_e32 v84, v113, v113
	v_fmac_f32_e32 v197, v192, v192
	v_fmac_f32_e32 v84, v112, v112
	v_add_f32_e32 v84, v197, v84
	v_add_f32_e32 v154, v196, v84
	v_mul_f32_e32 v84, v87, v87
	v_mul_f32_e32 v85, v89, v89
	v_fmac_f32_e32 v84, v86, v86
	v_fmac_f32_e32 v85, v88, v88
	v_lshl_add_u64 v[86:87], s[50:51], 0, v[82:83]
	v_add_f32_e32 v112, v84, v85
	global_load_dwordx4 v[82:85], v[86:87], off offset:16
	s_nop 0
	global_load_dwordx4 v[86:89], v[86:87], off
	v_mul_f32_e32 v113, v129, v129
	v_mul_f32_e32 v127, v127, v127
	v_fmac_f32_e32 v113, v128, v128
	v_fmac_f32_e32 v127, v126, v126
	v_add_f32_e32 v113, v113, v127
	s_mov_b64 s[30:31], 0x10200
	v_add_f32_e32 v180, v112, v113
	v_lshl_add_u64 v[112:113], v[160:161], 0, s[30:31]
	global_load_dwordx4 v[126:129], v[168:169], off offset:512
	s_nop 0
	global_load_dwordx4 v[168:171], v[112:113], off offset:16
	s_waitcnt vmcnt(13)
	v_pk_fma_f32 v[80:81], v[80:81], v[136:137], v[104:105]
	v_pk_fma_f32 v[78:79], v[78:79], v[134:135], v[102:103]
	v_mul_f32_e32 v103, v81, v81
	v_mul_f32_e32 v102, v79, v79
	s_waitcnt vmcnt(12)
	v_pk_fma_f32 v[76:77], v[76:77], v[132:133], v[110:111]
	v_pk_fma_f32 v[74:75], v[74:75], v[130:131], v[108:109]
	v_fmac_f32_e32 v102, v78, v78
	v_fmac_f32_e32 v103, v80, v80
	v_add_f32_e32 v102, v102, v103
	v_mul_f32_e32 v103, v75, v75
	v_mul_f32_e32 v104, v77, v77
	v_fmac_f32_e32 v103, v74, v74
	v_fmac_f32_e32 v104, v76, v76
	v_add_f32_e32 v103, v103, v104
	v_add_f32_e32 v108, v102, v103
	v_pk_mul_f32 v[80:81], v[144:145], v[80:81]
	v_pk_mul_f32 v[78:79], v[142:143], v[78:79]
	v_pk_mul_f32 v[102:103], v[140:141], v[76:77]
	v_pk_mul_f32 v[76:77], v[138:139], v[74:75]
	v_cvt_pk_bf16_f32 v74, v78, v79
	v_cvt_pk_bf16_f32 v75, v80, v81
	v_cvt_pk_bf16_f32 v76, v76, v77
	v_cvt_pk_bf16_f32 v77, v102, v103
	s_waitcnt vmcnt(11)
	v_pk_fma_f32 v[72:73], v[72:73], v[136:137], v[186:187]
	v_pk_fma_f32 v[70:71], v[70:71], v[134:135], v[184:185]
	s_cselect_b32 s100, 1, 0
	s_cmp_lg_u32 s98, 0
	s_cbranch_scc1 .Lwt_p4_6_a
	global_store_dwordx4 v[194:195], v[74:77], off
	s_branch .Lwt_p4_6_b
.Lwt_p4_6_a:
	global_store_dwordx4 v[194:195], v[74:77], off sc1
.Lwt_p4_6_b:
	s_cmp_lg_u32 s100, 0
	v_mul_f32_e32 v78, v71, v71
	v_mul_f32_e32 v79, v73, v73
	s_waitcnt vmcnt(11)
	v_pk_fma_f32 v[74:75], v[64:65], v[132:133], v[190:191]
	v_pk_fma_f32 v[76:77], v[62:63], v[130:131], v[188:189]
	v_fmac_f32_e32 v78, v70, v70
	v_fmac_f32_e32 v79, v72, v72
	v_pk_mul_f32 v[64:65], v[144:145], v[72:73]
	v_pk_mul_f32 v[62:63], v[142:143], v[70:71]
	v_pk_mul_f32 v[70:71], v[140:141], v[74:75]
	v_pk_mul_f32 v[72:73], v[138:139], v[76:77]
	v_cvt_pk_bf16_f32 v62, v62, v63
	v_cvt_pk_bf16_f32 v63, v64, v65
	v_cvt_pk_bf16_f32 v64, v72, v73
	v_cvt_pk_bf16_f32 v65, v70, v71
	s_cselect_b32 s100, 1, 0
	s_cmp_lg_u32 s98, 0
	s_cbranch_scc1 .Lwt_p4_7_a
	global_store_dwordx4 v[194:195], v[62:65], off offset:2048
	s_branch .Lwt_p4_7_b
.Lwt_p4_7_a:
	global_store_dwordx4 v[194:195], v[62:65], off offset:2048 sc1
.Lwt_p4_7_b:
	s_cmp_lg_u32 s100, 0
	global_load_dwordx4 v[62:65], v[164:165], off offset:512
	s_mov_b64 s[30:31], 0x20200
	v_lshl_add_u64 v[70:71], v[160:161], 0, s[30:31]
	global_load_dwordx4 v[70:73], v[70:71], off offset:16
	v_mul_f32_e32 v77, v77, v77
	v_mul_f32_e32 v75, v75, v75
	v_fmac_f32_e32 v77, v76, v76
	v_fmac_f32_e32 v75, v74, v74
	v_add_f32_e32 v78, v78, v79
	v_add_f32_e32 v74, v77, v75
	s_mov_b64 s[30:31], 0x30200
	v_add_f32_e32 v109, v78, v74
	v_lshl_add_u64 v[78:79], v[160:161], 0, s[30:31]
	global_load_dwordx4 v[74:77], v[166:167], off offset:512
	s_nop 0
	global_load_dwordx4 v[78:81], v[78:79], off offset:16
	s_waitcnt vmcnt(11)
	v_pk_fma_f32 v[60:61], v[60:61], v[92:93], v[120:121]
	s_waitcnt vmcnt(10)
	v_pk_fma_f32 v[68:69], v[68:69], v[96:97], v[124:125]
	v_pk_fma_f32 v[66:67], v[66:67], v[94:95], v[122:123]
	v_pk_fma_f32 v[58:59], v[58:59], v[90:91], v[118:119]
	v_mul_f32_e32 v102, v67, v67
	v_mul_f32_e32 v103, v69, v69
	v_fmac_f32_e32 v102, v66, v66
	v_fmac_f32_e32 v103, v68, v68
	v_mul_f32_e32 v111, v59, v59
	v_mul_f32_e32 v112, v61, v61
	v_add_f32_e32 v110, v102, v103
	v_fmac_f32_e32 v111, v58, v58
	v_fmac_f32_e32 v112, v60, v60
	s_waitcnt vmcnt(8)
	v_pk_mul_f32 v[66:67], v[86:87], v[66:67]
	v_pk_mul_f32 v[102:103], v[84:85], v[60:61]
	v_pk_mul_f32 v[60:61], v[82:83], v[58:59]
	v_cvt_pk_bf16_f32 v58, v66, v67
	v_add_co_u32_e32 v66, vcc, s40, v162
	s_mov_b32 s9, 0x11000
	s_nop 0
	v_addc_co_u32_e32 v67, vcc, 0, v163, vcc
	v_pk_mul_f32 v[68:69], v[88:89], v[68:69]
	v_cvt_pk_bf16_f32 v60, v60, v61
	v_cvt_pk_bf16_f32 v61, v102, v103
	v_add_co_u32_e32 v102, vcc, s9, v162
	v_cvt_pk_bf16_f32 v59, v68, v69
	s_nop 0
	v_addc_co_u32_e32 v103, vcc, 0, v163, vcc
	s_cselect_b32 s100, 1, 0
	s_cmp_lg_u32 s98, 0
	s_cbranch_scc1 .Lwt_p4_8_a
	global_store_dwordx4 v[102:103], v[58:61], off offset:-4096
	s_branch .Lwt_p4_8_b
.Lwt_p4_8_a:
	global_store_dwordx4 v[102:103], v[58:61], off offset:-4096 sc1
; __device__ __forceinline__ unsigned cvt_pk(float lo, float hi) { f32x2_t v = {lo, hi}; bf16x2_t b = __builtin_convertvector(v, bf16x2_t); return __builtin_bit_cast(unsigned, b); }
; #define EO_LOADG(bj) do { _Pragma("unroll") for (int n = 0; n < 2; ++n) { const int c_ = u.pn * 256 + (bj) * 128 + cl + 4 * n; g1a[bj][n] = *(const f32x4*)(g1t + b * D + c_); G2a[bj][n] = *(const f32x4*)(G2t + b * D + c_); } } while (0)
; #define EO_LOADB(k) do { _Pragma("unroll") for (int mm = 0; mm < 2; ++mm) { const char* xr = xb + (size_t)(((((k) >> 1) & 1) * 128 + (2 * ((k) & 1) + mm) * 16) * D + ((k) >> 2) * 128) * 4; \
;             xv[(k) & 1][mm][0] = *(const f32x4*)(xr + loff); xv[(k) & 1][mm][1] = *(const f32x4*)(xr + 16 + loff); } } while (0)
;     __device__ __forceinline__ void operator()(AccRef acc, const pg8::Unit& u, int wr, int wc, int fr_, int fq_) const {
;     ...
;         EO_LOADG(0); EO_LOADB(0);
; #pragma unroll
;         for (int k = 0; k < 8; ++k) {
;             const int bj = k >> 2, ai = (k >> 1) & 1;
;             if (k + 1 < 8) EO_LOADB(k + 1);
;             if (k == 3) EO_LOADG(1);
;             asm volatile("" ::: "memory");
; #pragma unroll
;             for (int mm = 0; mm < 2; ++mm) { const int m = 2 * (k & 1) + mm;
;                 const f32x4 v0 = xv[k & 1][mm][0] + g1a[bj][0] * acc[ai][bj][m][0], v1 = xv[k & 1][mm][1] + g1a[bj][1] * acc[ai][bj][m][1];
;                 ss[ai][m] += ((v0[0] * v0[0] + v0[1] * v0[1]) + (v0[2] * v0[2] + v0[3] * v0[3])) + ((v1[0] * v1[0] + v1[1] * v1[1]) + (v1[2] * v1[2] + v1[3] * v1[3]));
;                 const f32x4 h0 = v0 * G2a[bj][0], h1 = v1 * G2a[bj][1]; v4u w; w.x = cvt_pk(h0[0], h0[1]); w.y = cvt_pk(h0[2], h0[3]); w.z = cvt_pk(h1[0], h1[1]); w.w = cvt_pk(h1[2], h1[3]);
;                 *(v4u*)(xgb + (size_t)((2 * bj) << 15) + (size_t)((ai * 128 + m * 16) * 128) + xgl) = w;
;             }
.Lwt_p4_8_b:
	s_cmp_lg_u32 s100, 0
	s_waitcnt vmcnt(7)
	v_pk_fma_f32 v[68:69], v[52:53], v[92:93], v[170:171]
	v_pk_fma_f32 v[104:105], v[50:51], v[90:91], v[168:169]
	v_pk_fma_f32 v[58:59], v[56:57], v[96:97], v[128:129]
	v_pk_fma_f32 v[60:61], v[54:55], v[94:95], v[126:127]
	v_pk_mul_f32 v[52:53], v[88:89], v[58:59]
	v_pk_mul_f32 v[50:51], v[86:87], v[60:61]
	v_pk_mul_f32 v[54:55], v[84:85], v[68:69]
	v_pk_mul_f32 v[56:57], v[82:83], v[104:105]
	v_cvt_pk_bf16_f32 v50, v50, v51
	v_cvt_pk_bf16_f32 v51, v52, v53
	v_cvt_pk_bf16_f32 v52, v56, v57
	v_cvt_pk_bf16_f32 v53, v54, v55
	s_cselect_b32 s100, 1, 0
	s_cmp_lg_u32 s98, 0
	s_cbranch_scc1 .Lwt_p4_9_a
	global_store_dwordx4 v[66:67], v[50:53], off offset:2048
	s_branch .Lwt_p4_9_b
.Lwt_p4_9_a:
	global_store_dwordx4 v[66:67], v[50:53], off offset:2048 sc1
.Lwt_p4_9_b:
	s_cmp_lg_u32 s100, 0
	s_mov_b64 s[30:31], 0x80200
	v_lshl_add_u64 v[54:55], v[160:161], 0, s[30:31]
	global_load_dwordx4 v[50:53], v[116:117], off offset:512
	v_mul_f32_e32 v61, v61, v61
	global_load_dwordx4 v[54:57], v[54:55], off offset:16
	v_mul_f32_e32 v59, v59, v59
	v_fmac_f32_e32 v61, v60, v60
	v_fmac_f32_e32 v59, v58, v58
	v_add_f32_e32 v58, v61, v59
	v_mul_f32_e32 v59, v105, v105
	v_mul_f32_e32 v60, v69, v69
	v_add_f32_e32 v66, v111, v112
	v_fmac_f32_e32 v59, v104, v104
	v_fmac_f32_e32 v60, v68, v68
	v_add_f32_e32 v66, v110, v66
	v_add_f32_e32 v59, v59, v60
	s_mov_b64 s[30:31], 0x90200
	v_add_f32_e32 v110, v179, v66
	v_add_f32_e32 v58, v58, v59
	v_lshl_add_u64 v[66:67], v[160:161], 0, s[30:31]
	v_add_f32_e32 v104, v212, v58
	global_load_dwordx4 v[58:61], v[114:115], off offset:512
	s_nop 0
	global_load_dwordx4 v[66:69], v[66:67], off offset:16
	s_waitcnt vmcnt(9)
	v_pk_fma_f32 v[48:49], v[48:49], v[96:97], v[64:65]
	v_pk_fma_f32 v[46:47], v[46:47], v[94:95], v[62:63]
	v_mul_f32_e32 v63, v49, v49
	v_mul_f32_e32 v62, v47, v47
	s_waitcnt vmcnt(8)
	v_pk_fma_f32 v[44:45], v[44:45], v[92:93], v[72:73]
	v_pk_fma_f32 v[42:43], v[42:43], v[90:91], v[70:71]
	v_fmac_f32_e32 v62, v46, v46
	v_fmac_f32_e32 v63, v48, v48
	v_add_f32_e32 v62, v62, v63
	v_mul_f32_e32 v63, v43, v43
	v_mul_f32_e32 v64, v45, v45
	v_fmac_f32_e32 v63, v42, v42
	v_fmac_f32_e32 v64, v44, v44
	v_add_f32_e32 v63, v63, v64
	v_add_f32_e32 v64, v62, v63
	v_pk_mul_f32 v[48:49], v[88:89], v[48:49]
	v_pk_mul_f32 v[46:47], v[86:87], v[46:47]
	v_pk_mul_f32 v[62:63], v[84:85], v[44:45]
	v_pk_mul_f32 v[44:45], v[82:83], v[42:43]
	v_cvt_pk_bf16_f32 v42, v46, v47
	v_cvt_pk_bf16_f32 v43, v48, v49
	v_cvt_pk_bf16_f32 v44, v44, v45
	v_cvt_pk_bf16_f32 v45, v62, v63
	s_cselect_b32 s100, 1, 0
	s_cmp_lg_u32 s98, 0
	s_cbranch_scc1 .Lwt_p4_10_a
	global_store_dwordx4 v[102:103], v[42:45], off
	s_branch .Lwt_p4_10_b
.Lwt_p4_10_a:
	global_store_dwordx4 v[102:103], v[42:45], off sc1
.Lwt_p4_10_b:
	s_cmp_lg_u32 s100, 0
	s_waitcnt vmcnt(7)
	v_pk_fma_f32 v[46:47], v[36:37], v[92:93], v[80:81]
	v_pk_fma_f32 v[48:49], v[34:35], v[90:91], v[78:79]
	v_pk_fma_f32 v[42:43], v[40:41], v[96:97], v[76:77]
	v_pk_fma_f32 v[44:45], v[38:39], v[94:95], v[74:75]
	v_pk_mul_f32 v[36:37], v[88:89], v[42:43]
	v_pk_mul_f32 v[34:35], v[86:87], v[44:45]
	v_pk_mul_f32 v[38:39], v[84:85], v[46:47]
	v_pk_mul_f32 v[40:41], v[82:83], v[48:49]
	v_cvt_pk_bf16_f32 v34, v34, v35
	v_cvt_pk_bf16_f32 v35, v36, v37
	v_cvt_pk_bf16_f32 v36, v40, v41
	v_cvt_pk_bf16_f32 v37, v38, v39
	s_cselect_b32 s100, 1, 0
	s_cmp_lg_u32 s98, 0
	s_cbranch_scc1 .Lwt_p4_11_a
	global_store_dwordx4 v[102:103], v[34:37], off offset:2048
	s_branch .Lwt_p4_11_b
.Lwt_p4_11_a:
	global_store_dwordx4 v[102:103], v[34:37], off offset:2048 sc1
.Lwt_p4_11_b:
	s_cmp_lg_u32 s100, 0
	global_load_dwordx4 v[34:37], v[100:101], off offset:512
	s_mov_b64 s[30:31], 0xa0200
	v_lshl_add_u64 v[38:39], v[160:161], 0, s[30:31]
	global_load_dwordx4 v[38:41], v[38:39], off offset:16
	v_mul_f32_e32 v45, v45, v45
	v_mul_f32_e32 v43, v43, v43
	v_fmac_f32_e32 v45, v44, v44
	v_fmac_f32_e32 v43, v42, v42
	v_add_f32_e32 v42, v45, v43
	v_mul_f32_e32 v43, v49, v49
	v_mul_f32_e32 v44, v47, v47
	v_fmac_f32_e32 v43, v48, v48
	v_fmac_f32_e32 v44, v46, v46
	v_add_f32_e32 v43, v43, v44
	v_add_f32_e32 v42, v42, v43
	v_lshl_add_u64 v[46:47], v[160:161], 0, s[6:7]
	v_add_f32_e32 v63, v107, v42
	global_load_dwordx4 v[42:45], v[98:99], off offset:512
	s_nop 0
	global_load_dwordx4 v[46:49], v[46:47], off offset:16
	s_mov_b32 s9, 0x14000
	v_add_f32_e32 v62, v106, v64
	s_waitcnt vmcnt(9)
	v_pk_fma_f32 v[32:33], v[32:33], v[96:97], v[52:53]
	v_pk_fma_f32 v[30:31], v[30:31], v[94:95], v[50:51]
	s_waitcnt vmcnt(8)
	v_pk_fma_f32 v[50:51], v[28:29], v[92:93], v[56:57]
	v_pk_fma_f32 v[52:53], v[26:27], v[90:91], v[54:55]
	v_pk_mul_f32 v[28:29], v[88:89], v[32:33]
	v_pk_mul_f32 v[26:27], v[86:87], v[30:31]
	v_pk_mul_f32 v[54:55], v[84:85], v[50:51]
	v_cvt_pk_bf16_f32 v26, v26, v27
	v_cvt_pk_bf16_f32 v27, v28, v29
	v_cvt_pk_bf16_f32 v29, v54, v55
	v_add_co_u32_e32 v54, vcc, s9, v162
	v_pk_mul_f32 v[56:57], v[82:83], v[52:53]
	s_nop 0
	v_addc_co_u32_e32 v55, vcc, 0, v163, vcc
	v_cvt_pk_bf16_f32 v28, v56, v57
	v_add_co_u32_e32 v56, vcc, s59, v162
	s_waitcnt vmcnt(7)
	v_pk_fma_f32 v[24:25], v[24:25], v[96:97], v[60:61]
	v_addc_co_u32_e32 v57, vcc, 0, v163, vcc
	s_cselect_b32 s100, 1, 0
	s_cmp_lg_u32 s98, 0
	s_cbranch_scc1 .Lwt_p4_12_a
	global_store_dwordx4 v[56:57], v[26:29], off offset:-4096
	s_branch .Lwt_p4_12_b
.Lwt_p4_12_a:
	global_store_dwordx4 v[56:57], v[26:29], off offset:-4096 sc1
; __device__ __forceinline__ unsigned cvt_pk(float lo, float hi) { f32x2_t v = {lo, hi}; bf16x2_t b = __builtin_convertvector(v, bf16x2_t); return __builtin_bit_cast(unsigned, b); }
;     __device__ __forceinline__ void operator()(AccRef acc, const pg8::Unit& u, int wr, int wc, int fr_, int fq_) const {
;     ...
;             for (int mm = 0; mm < 2; ++mm) { const int m = 2 * (k & 1) + mm;
;                 const f32x4 v0 = xv[k & 1][mm][0] + g1a[bj][0] * acc[ai][bj][m][0], v1 = xv[k & 1][mm][1] + g1a[bj][1] * acc[ai][bj][m][1];
;                 ss[ai][m] += ((v0[0] * v0[0] + v0[1] * v0[1]) + (v0[2] * v0[2] + v0[3] * v0[3])) + ((v1[0] * v1[0] + v1[1] * v1[1]) + (v1[2] * v1[2] + v1[3] * v1[3]));
;                 const f32x4 h0 = v0 * G2a[bj][0], h1 = v1 * G2a[bj][1]; v4u w; w.x = cvt_pk(h0[0], h0[1]); w.y = cvt_pk(h0[2], h0[3]); w.z = cvt_pk(h1[0], h1[1]); w.w = cvt_pk(h1[2], h1[3]);
;                 *(v4u*)(xgb + (size_t)((2 * bj) << 15) + (size_t)((ai * 128 + m * 16) * 128) + xgl) = w;
;             }
;             asm volatile("" ::: "memory");
;         }
;     ...
; #pragma unroll
;         for (int ai = 0; ai < 2; ++ai)
; #pragma unroll
;             for (int m = 0; m < 4; ++m) ss[ai][m] = red_sum_16_32(ss[ai][m]);
;         if (fq == 0) {
; #pragma unroll
;             for (int ai = 0; ai < 2; ++ai)
; #pragma unroll
;                 for (int m = 0; m < 4; ++m) atomicAdd(rss2 + grow0 + ai * 128 + m * 16, ss[ai][m] * asc);
.Lwt_p4_12_b:
	s_cmp_lg_u32 s100, 0
	v_pk_fma_f32 v[22:23], v[22:23], v[94:95], v[58:59]
	v_cmp_eq_u32_e32 vcc, 0, v177
	s_waitcnt vmcnt(7)
	v_pk_fma_f32 v[26:27], v[20:21], v[92:93], v[68:69]
	v_pk_fma_f32 v[28:29], v[18:19], v[90:91], v[66:67]
	v_pk_mul_f32 v[20:21], v[88:89], v[24:25]
	v_pk_mul_f32 v[18:19], v[86:87], v[22:23]
	v_pk_mul_f32 v[58:59], v[84:85], v[26:27]
	v_pk_mul_f32 v[60:61], v[82:83], v[28:29]
	v_cvt_pk_bf16_f32 v18, v18, v19
	v_cvt_pk_bf16_f32 v19, v20, v21
	v_cvt_pk_bf16_f32 v20, v60, v61
	v_cvt_pk_bf16_f32 v21, v58, v59
	s_cselect_b32 s100, 1, 0
	s_cmp_lg_u32 s98, 0
	s_cbranch_scc1 .Lwt_p4_13_a
	global_store_dwordx4 v[54:55], v[18:21], off offset:2048
	s_branch .Lwt_p4_13_b
.Lwt_p4_13_a:
	global_store_dwordx4 v[54:55], v[18:21], off offset:2048 sc1
.Lwt_p4_13_b:
	s_cmp_lg_u32 s100, 0
	s_waitcnt vmcnt(5)
	v_pk_fma_f32 v[16:17], v[16:17], v[96:97], v[36:37]
	v_mul_f32_e32 v18, v23, v23
	v_mul_f32_e32 v19, v25, v25
	v_fmac_f32_e32 v18, v22, v22
	v_fmac_f32_e32 v19, v24, v24
	v_add_f32_e32 v18, v18, v19
	v_mul_f32_e32 v19, v29, v29
	v_mul_f32_e32 v20, v27, v27
	v_fmac_f32_e32 v19, v28, v28
	v_fmac_f32_e32 v20, v26, v26
	v_add_f32_e32 v19, v19, v20
	v_add_f32_e32 v18, v18, v19
	v_add_f32_e32 v20, v180, v18
	v_mul_f32_e32 v18, v31, v31
	v_mul_f32_e32 v19, v33, v33
	v_fmac_f32_e32 v18, v30, v30
	v_fmac_f32_e32 v19, v32, v32
	v_add_f32_e32 v18, v18, v19
	v_mul_f32_e32 v19, v53, v53
	v_mul_f32_e32 v21, v51, v51
	v_fmac_f32_e32 v19, v52, v52
	v_fmac_f32_e32 v21, v50, v50
	v_add_f32_e32 v19, v19, v21
	v_add_f32_e32 v18, v18, v19
	v_pk_fma_f32 v[14:15], v[14:15], v[94:95], v[34:35]
	v_add_f32_e32 v21, v154, v18
	v_mul_f32_e32 v18, v15, v15
	v_mul_f32_e32 v19, v17, v17
	s_waitcnt vmcnt(4)
	v_pk_fma_f32 v[12:13], v[12:13], v[92:93], v[40:41]
	v_pk_fma_f32 v[10:11], v[10:11], v[90:91], v[38:39]
	v_fmac_f32_e32 v18, v14, v14
	v_fmac_f32_e32 v19, v16, v16
	v_add_f32_e32 v18, v18, v19
	v_mul_f32_e32 v19, v11, v11
	v_mul_f32_e32 v22, v13, v13
	v_fmac_f32_e32 v19, v10, v10
	v_fmac_f32_e32 v22, v12, v12
	v_add_f32_e32 v19, v19, v22
	v_add_f32_e32 v18, v18, v19
	v_add_f32_e32 v22, v108, v18
	v_pk_mul_f32 v[16:17], v[88:89], v[16:17]
	v_pk_mul_f32 v[14:15], v[86:87], v[14:15]
	v_pk_mul_f32 v[18:19], v[84:85], v[12:13]
	v_pk_mul_f32 v[12:13], v[82:83], v[10:11]
	v_cvt_pk_bf16_f32 v10, v14, v15
	v_cvt_pk_bf16_f32 v11, v16, v17
	v_cvt_pk_bf16_f32 v12, v12, v13
	v_cvt_pk_bf16_f32 v13, v18, v19
	s_waitcnt vmcnt(3)
	v_pk_fma_f32 v[8:9], v[8:9], v[96:97], v[44:45]
	v_pk_fma_f32 v[6:7], v[6:7], v[94:95], v[42:43]
	s_cselect_b32 s100, 1, 0
	s_cmp_lg_u32 s98, 0
	s_cbranch_scc1 .Lwt_p4_14_a
	global_store_dwordx4 v[56:57], v[10:13], off
	s_branch .Lwt_p4_14_b
.Lwt_p4_14_a:
	global_store_dwordx4 v[56:57], v[10:13], off sc1
.Lwt_p4_14_b:
	s_cmp_lg_u32 s100, 0
	s_waitcnt vmcnt(3)
	v_pk_fma_f32 v[4:5], v[4:5], v[92:93], v[48:49]
	v_pk_fma_f32 v[2:3], v[2:3], v[90:91], v[46:47]
	v_mul_f32_e32 v10, v7, v7
	v_mul_f32_e32 v11, v9, v9
	v_fmac_f32_e32 v10, v6, v6
	v_fmac_f32_e32 v11, v8, v8
	v_add_f32_e32 v10, v10, v11
	v_mul_f32_e32 v11, v3, v3
	v_mul_f32_e32 v12, v5, v5
	v_fmac_f32_e32 v11, v2, v2
	v_fmac_f32_e32 v12, v4, v4
	v_add_f32_e32 v11, v11, v12
	v_add_f32_e32 v10, v10, v11
	v_add_f32_e32 v16, v109, v10
	v_pk_mul_f32 v[8:9], v[88:89], v[8:9]
	v_pk_mul_f32 v[6:7], v[86:87], v[6:7]
	v_pk_mul_f32 v[10:11], v[84:85], v[4:5]
	v_pk_mul_f32 v[4:5], v[82:83], v[2:3]
	v_cvt_pk_bf16_f32 v2, v6, v7
	v_cvt_pk_bf16_f32 v3, v8, v9
	v_cvt_pk_bf16_f32 v4, v4, v5
	v_cvt_pk_bf16_f32 v5, v10, v11
	s_cselect_b32 s100, 1, 0
	s_cmp_lg_u32 s98, 0
	s_cbranch_scc1 .Lwt_p4_15_a
	global_store_dwordx4 v[56:57], v[2:5], off offset:2048
	s_branch .Lwt_p4_15_b
.Lwt_p4_15_a:
	global_store_dwordx4 v[56:57], v[2:5], off offset:2048 sc1
.Lwt_p4_15_b:
	s_cmp_lg_u32 s100, 0
	v_mov_b32_e32 v6, v62
	v_mov_b32_e32 v8, v63
	v_mov_b32_e32 v2, v110
	s_nop 1
	v_permlane16_swap_b32 v110, v2
	v_mov_b32_e32 v4, v104
	v_add_f32_e32 v2, v110, v2
	v_mov_b32_e32 v3, v2
	s_nop 1
	v_permlane32_swap_b32 v2, v3
	s_nop 1
	v_permlane16_swap_b32 v104, v4
	v_mov_b32_e32 v10, v21
	v_add_f32_e32 v4, v104, v4
	v_mov_b32_e32 v5, v4
	s_nop 1
	v_permlane32_swap_b32 v4, v5
	s_nop 1
	v_permlane16_swap_b32 v62, v6
	v_mov_b32_e32 v12, v20
	v_add_f32_e32 v6, v62, v6
	v_mov_b32_e32 v7, v6
	s_nop 1
	v_permlane32_swap_b32 v6, v7
	s_nop 1
	v_permlane16_swap_b32 v63, v8
	v_mov_b32_e32 v14, v22
	v_add_f32_e32 v8, v63, v8
	v_mov_b32_e32 v9, v8
	s_nop 1
	v_permlane32_swap_b32 v8, v9
	s_nop 1
	v_permlane16_swap_b32 v21, v10
	v_mov_b32_e32 v17, v16
	v_add_f32_e32 v10, v21, v10
	v_mov_b32_e32 v11, v10
	s_nop 1
	v_permlane32_swap_b32 v10, v11
	s_nop 1
	v_permlane16_swap_b32 v20, v12
	s_nop 0
	v_add_f32_e32 v12, v20, v12
	v_mov_b32_e32 v13, v12
	s_nop 1
	v_permlane32_swap_b32 v12, v13
	s_nop 1
	v_permlane16_swap_b32 v22, v14
	s_nop 0
	v_add_f32_e32 v14, v22, v14
	v_mov_b32_e32 v15, v14
	s_nop 1
	v_permlane32_swap_b32 v14, v15
	s_nop 1
	v_permlane16_swap_b32 v16, v17
	s_nop 0
	v_add_f32_e32 v16, v16, v17
	v_mov_b32_e32 v17, v16
	s_nop 1
	v_permlane32_swap_b32 v16, v17
	s_and_saveexec_b64 s[30:31], vcc
	s_cbranch_execz .LBB0_453
	v_lshl_add_u32 v18, s46, 8, v178
	v_ashrrev_i32_e32 v19, 31, v18
	v_add_f32_e32 v4, v4, v5
	v_add_f32_e32 v5, v2, v3
	v_lshl_add_u64 v[2:3], v[18:19], 2, s[20:21]
	v_add_f32_e32 v16, v16, v17
	v_add_f32_e32 v14, v14, v15
	v_add_f32_e32 v12, v12, v13
	v_add_f32_e32 v10, v10, v11
	v_add_f32_e32 v8, v8, v9
	v_add_f32_e32 v6, v6, v7
	global_atomic_add_f32 v[2:3], v5, off
	global_atomic_add_f32 v[2:3], v4, off offset:64
	global_atomic_add_f32 v[2:3], v6, off offset:128
	global_atomic_add_f32 v[2:3], v8, off offset:192
	global_atomic_add_f32 v[2:3], v10, off offset:512
	global_atomic_add_f32 v[2:3], v12, off offset:576
	global_atomic_add_f32 v[2:3], v14, off offset:640
	global_atomic_add_f32 v[2:3], v16, off offset:704
